# queue draw for the next round no longer waited at the draw site: atomic returns into the qnext register, retired by the unit's first counted vmcnt wait
# speedup vs baseline: 1.0033x; 1.0033x over previous
.LBB0_290:
	v_mov_b32_e32 v0, s87
	s_waitcnt lgkmcnt(0)
	s_barrier
	ds_read_b32 v0, v0
	v_readlane_b32 s2, v245, 12
	s_waitcnt lgkmcnt(0)
	v_readfirstlane_b32 s46, v0
	s_cmp_ge_i32 s46, s2
	s_cselect_b64 s[72:73], -1, 0
	s_and_b64 vcc, exec, s[72:73]
	s_cbranch_vccnz .LBB0_285
	s_and_b64 vcc, exec, s[92:93]
	s_cbranch_vccnz .LBB0_297
	v_mov_b32_e32 v0, v220
	s_nop 0
	v_cmp_eq_u32_e32 vcc, 0, v0
	s_and_saveexec_b64 s[2:3], vcc
	s_cbranch_execz .LBB0_296
	s_mov_b64 s[12:13], exec
	v_mbcnt_lo_u32_b32 v0, s12, 0
	v_mbcnt_hi_u32_b32 v0, s13, v0
	v_cmp_eq_u32_e32 vcc, 0, v0
	s_and_saveexec_b64 s[4:5], vcc
	s_cbranch_execz .LBB0_295
	s_bcnt1_i32_b64 s12, s[12:13]
	v_mov_b32_e32 v2, s12
	global_atomic_add v184, v1, v2, s[70:71] sc0
.LBB0_295:
	s_or_b64 exec, exec, s[4:5]
.LBB0_296:
	s_or_b64 exec, exec, s[2:3]
